# two polls in flight in the generated barrier spin loops, on top of the split-barrier version
# speedup vs baseline: 1.0016x; 1.0016x over previous
.Lnb3_wait:
	v_readlane_b32 s15, v219, 30
	s_nop 1
	s_cmp_lt_u32 s15, 0x100
	s_cbranch_scc1 .Lnb3_skip
	v_mov_b32_e32 v1, s14
	s_mov_b32 s15, 0
	global_load_dword v2, v1, s[0:1] sc1
